# v086 + the last 3840 items of the layer-1 in/out projection weights also deferred into the down-L0 idle tail
# baseline (speedup 1.0000x reference)
; #define LAS __attribute__((address_space(3)))
; __device__ __forceinline__ void p0_weights(KAP a, LAS unsigned char* lds, int gw, int NGW, int wave, int lane) {
;     LAS float* scr = (LAS float*)(lds + wave * 8704);
;     unsigned char* ws = a->ws;
;     constexpr int I_TOTAL = (2048 / 64) * (2624 / 32) + (512 / 64) * (1536 / 32) + (512 / 64) * (2048 / 32) + 2 * (2048 / 64) * (2048 / 32) + (2048 / 64) * (4608 / 32)
;                           + 4 * (2048 / 64) * (DFF / 32) + 2 * (DFF / 64) * (2048 / 32);
;     for (int item = gw; item < I_TOTAL; item += NGW) {
;         int it = item;
;         if (conv_matrix(it, a->in[13], 2048, 2624, (bf16*)(ws + WS_WIN0), 0, scr, lane)) continue;
;         if (conv_matrix(it, a->in[19], 512, 1536, (bf16*)(ws + WS_WUQ), 0, scr, lane, 0.07216878364870322f * 1.4426950408889634f)) continue;
;         if (conv_matrix(it, a->in[20], 512, 2048, (bf16*)(ws + WS_WUKV), 0, scr, lane)) continue;
;         if (conv_matrix(it, a->in[14], 2048, 2048, (bf16*)(ws + WS_WOUT0), 0, scr, lane)) continue;
;         if (conv_matrix(it, a->in[21], 2048, 4608, (bf16*)(ws + WS_WIN1), 0, scr, lane)) continue;
;         if (conv_matrix(it, a->in[22], 2048, 2048, (bf16*)(ws + WS_WOUT1), 0, scr, lane)) continue;
;         if (conv_matrix(it, a->in[10], 2048, DFF, (bf16*)(ws + WS_WGU), 1, scr, lane)) continue;
;         if (conv_matrix(it, a->in[10] + (size_t)2048 * DFF, 2048, DFF, (bf16*)(ws + WS_WGU + 44 * MiB), 1, scr, lane)) continue;
;         if (conv_matrix(it, a->in[11], 2048, DFF, (bf16*)(ws + WS_WGU), 2, scr, lane)) continue;
;         if (conv_matrix(it, a->in[11] + (size_t)2048 * DFF, 2048, DFF, (bf16*)(ws + WS_WGU + 44 * MiB), 2, scr, lane)) continue;
;         if (conv_matrix(it, a->in[12], DFF, 2048, (bf16*)(ws + WS_WD), 0, scr, lane)) continue;
;         conv_matrix(it, a->in[12] + (size_t)2048 * DFF, DFF, 2048, (bf16*)(ws + WS_WD + 22 * MiB), 0, scr, lane);
;     }
; }
.LBB0_36:
	v_mbcnt_lo_u32_b32 v2, -1, 0
	v_mbcnt_hi_u32_b32 v2, -1, v2
	s_lshl_b32 s5, s87, 3
	v_add_u32_e32 v0, s93, v2
	s_lshl_b32 s33, s74, 3
	v_readfirstlane_b32 s4, v0
	s_ashr_i32 s6, s4, 6
	s_add_i32 s99, s6, s5
	v_writelane_b32 v253, s5, 2
	s_mov_b64 s[4:5], s[0:1]
	s_cmp_gt_i32 s99, 0x62bf
	s_cbranch_scc1 .LBB0_119
	s_load_dwordx2 s[8:9], s[4:5], 0xf0
	v_bfe_u32 v0, v2, 5, 1
	v_and_b32_e32 v28, 31, v2
	v_bfe_u32 v1, v2, 3, 3
	v_lshlrev_b32_e32 v2, 3, v2
	v_and_b32_e32 v2, 56, v2
	v_mov_b32_e32 v3, 0
	v_mul_u32_u24_e32 v6, 0x84, v2
	v_lshlrev_b32_e32 v2, 1, v2
	s_mul_i32 s10, s6, 0x2200
	s_waitcnt lgkmcnt(0)
	v_lshl_add_u64 v[22:23], s[8:9], 0, v[2:3]
	s_mov_b64 s[6:7], 0x100000
	s_add_i32 s11, s10, 0
	v_lshl_add_u64 v[4:5], v[22:23], 0, s[6:7]
	v_lshlrev_b32_e32 v2, 2, v1
	s_mov_b64 s[6:7], 0xc00000
	v_add3_u32 v44, s11, v6, v2
	v_lshl_add_u64 v[6:7], v[22:23], 0, s[6:7]
	s_mov_b64 s[6:7], 0xe00000
	v_lshl_add_u64 v[8:9], v[22:23], 0, s[6:7]
	s_mov_b64 s[6:7], 0x1000000
	v_lshl_add_u64 v[10:11], v[22:23], 0, s[6:7]
	s_mov_b64 s[6:7], 0x1800000
	v_lshl_add_u64 v[12:13], v[22:23], 0, s[6:7]
	s_mov_b64 s[6:7], 0x2a00000
	v_lshl_add_u64 v[14:15], v[22:23], 0, s[6:7]
	s_mov_b64 s[6:7], 0x3200000
	v_lshl_add_u64 v[16:17], v[22:23], 0, s[6:7]
	s_mov_b64 s[6:7], 0x5e00000
	v_lshl_add_u64 v[18:19], v[22:23], 0, s[6:7]
	s_mov_b64 s[6:7], 0x8a00000
	v_mul_u32_u24_e32 v2, 0x84, v0
	v_lshl_add_u64 v[20:21], v[22:23], 0, s[6:7]
	s_mov_b64 s[6:7], 0xa000000
	v_or_b32_e32 v2, s10, v2
	v_lshlrev_b32_e32 v24, 2, v28
	v_or_b32_e32 v45, 8, v1
	v_or_b32_e32 v46, 16, v1
	v_or_b32_e32 v47, 24, v1
	v_lshl_add_u64 v[22:23], v[22:23], 0, s[6:7]
	v_add3_u32 v48, v2, v24, 0
	v_mov_b32_e32 v25, v3
	v_or_b32_e32 v49, 14, v0
	v_or_b32_e32 v50, 12, v0
	v_or_b32_e32 v51, 10, v0
	v_or_b32_e32 v52, 8, v0
	v_or_b32_e32 v53, 6, v0
	v_or_b32_e32 v54, 4, v0
	v_or_b32_e32 v55, 2, v0
	v_or_b32_e32 v26, 0x2c00000, v24
	v_mov_b32_e32 v27, v3
	s_movk_i32 s23, 0x2900
	s_movk_i32 s24, 0x7fff
	s_mov_b32 s25, 0xffff0000
	s_movk_i32 s26, 0x1800
	s_movk_i32 s27, 0x4800
	s_movk_i32 s28, 0x1600
	s_movk_i32 s29, 0x5800
	s_mov_b64 s[6:7], 0x2c00000
	v_lshlrev_b32_e32 v2, 2, v28
	v_mov_b32_e32 v56, 0x4800
	v_mov_b32_e32 v57, 0x5800
	s_branch .LBB0_39
.LBB0_38:
	s_add_i32 s99, s99, s33
	s_cmp_lt_i32 s99, 0x62c0
	s_cbranch_scc0 .LBB0_119
.LBB0_39:
	s_mov_b32 s22, s99
	s_cmp_ge_i32 s99, 0x20c0
	s_cselect_b32 s98, 0xf00, 0
	s_add_i32 s22, s22, s98
	s_cmp_ge_i32 s99, 0x36c0
	s_cselect_b32 s98, 0x1600, 0
	s_add_i32 s22, s22, s98
	s_cmp_ge_i32 s99, 0x4cc0
	s_cselect_b32 s98, 0x1600, 0
	s_add_i32 s22, s22, s98
	s_cmpk_gt_i32 s22, 0xa3f
	s_waitcnt lgkmcnt(0)
	s_cselect_b64 s[8:9], -1, 0
	s_cmpk_lt_i32 s22, 0xa40
	s_mov_b64 s[10:11], -1
	s_cbranch_scc0 .LBB0_42
	s_andn2_b64 vcc, exec, s[10:11]
	s_cbranch_vccz .LBB0_43

; #define LAS __attribute__((address_space(3)))
; __device__ __forceinline__ void p0_weights(KAP a, LAS unsigned char* lds, int gw, int NGW, int wave, int lane) {
;     LAS float* scr = (LAS float*)(lds + wave * 8704);
;     unsigned char* ws = a->ws;
;     constexpr int I_TOTAL = (2048 / 64) * (2624 / 32) + (512 / 64) * (1536 / 32) + (512 / 64) * (2048 / 32) + 2 * (2048 / 64) * (2048 / 32) + (2048 / 64) * (4608 / 32)
;                           + 4 * (2048 / 64) * (DFF / 32) + 2 * (DFF / 64) * (2048 / 32);
;     for (int item = gw; item < I_TOTAL; item += NGW) {
;         int it = item;
;         if (conv_matrix(it, a->in[13], 2048, 2624, (bf16*)(ws + WS_WIN0), 0, scr, lane)) continue;
;         if (conv_matrix(it, a->in[19], 512, 1536, (bf16*)(ws + WS_WUQ), 0, scr, lane, 0.07216878364870322f * 1.4426950408889634f)) continue;
;         if (conv_matrix(it, a->in[20], 512, 2048, (bf16*)(ws + WS_WUKV), 0, scr, lane)) continue;
;         if (conv_matrix(it, a->in[14], 2048, 2048, (bf16*)(ws + WS_WOUT0), 0, scr, lane)) continue;
;         if (conv_matrix(it, a->in[21], 2048, 4608, (bf16*)(ws + WS_WIN1), 0, scr, lane)) continue;
;         if (conv_matrix(it, a->in[22], 2048, 2048, (bf16*)(ws + WS_WOUT1), 0, scr, lane)) continue;
;         if (conv_matrix(it, a->in[10], 2048, DFF, (bf16*)(ws + WS_WGU), 1, scr, lane)) continue;
;         if (conv_matrix(it, a->in[10] + (size_t)2048 * DFF, 2048, DFF, (bf16*)(ws + WS_WGU + 44 * MiB), 1, scr, lane)) continue;
;         if (conv_matrix(it, a->in[11], 2048, DFF, (bf16*)(ws + WS_WGU), 2, scr, lane)) continue;
;         if (conv_matrix(it, a->in[11] + (size_t)2048 * DFF, 2048, DFF, (bf16*)(ws + WS_WGU + 44 * MiB), 2, scr, lane)) continue;
;         if (conv_matrix(it, a->in[12], DFF, 2048, (bf16*)(ws + WS_WD), 0, scr, lane)) continue;
;         conv_matrix(it, a->in[12] + (size_t)2048 * DFF, DFF, 2048, (bf16*)(ws + WS_WD + 22 * MiB), 0, scr, lane);
;     }
; }
.Ldfa_39:
	s_add_i32 s22, s99, 0x20c0
	s_cmp_ge_i32 s99, 0xf00
	s_cselect_b32 s98, 0x1600, 0
	s_add_i32 s22, s22, s98
	s_cmp_ge_i32 s99, 0x2500
	s_cselect_b32 s98, 0x1600, 0
	s_add_i32 s22, s22, s98
	s_cmp_ge_i32 s99, 0x3b00
	s_cselect_b32 s98, 0x1600, 0
	s_add_i32 s22, s22, s98
	s_cmpk_gt_i32 s22, 0xa3f
	s_waitcnt lgkmcnt(0)
	s_cselect_b64 s[8:9], -1, 0
	s_cmpk_lt_i32 s22, 0xa40
	s_mov_b64 s[10:11], -1
	s_cbranch_scc0 .Ldfa_42
	s_andn2_b64 vcc, exec, s[10:11]
	s_cbranch_vccz .Ldfa_43

; #define LAS __attribute__((address_space(3)))
; __device__ __forceinline__ void p0_weights(KAP a, LAS unsigned char* lds, int gw, int NGW, int wave, int lane) {
;     LAS float* scr = (LAS float*)(lds + wave * 8704);
;     unsigned char* ws = a->ws;
;     constexpr int I_TOTAL = (2048 / 64) * (2624 / 32) + (512 / 64) * (1536 / 32) + (512 / 64) * (2048 / 32) + 2 * (2048 / 64) * (2048 / 32) + (2048 / 64) * (4608 / 32)
;                           + 4 * (2048 / 64) * (DFF / 32) + 2 * (DFF / 64) * (2048 / 32);
;     for (int item = gw; item < I_TOTAL; item += NGW) {
;         int it = item;
;         if (conv_matrix(it, a->in[13], 2048, 2624, (bf16*)(ws + WS_WIN0), 0, scr, lane)) continue;
;         if (conv_matrix(it, a->in[19], 512, 1536, (bf16*)(ws + WS_WUQ), 0, scr, lane, 0.07216878364870322f * 1.4426950408889634f)) continue;
;         if (conv_matrix(it, a->in[20], 512, 2048, (bf16*)(ws + WS_WUKV), 0, scr, lane)) continue;
;         if (conv_matrix(it, a->in[14], 2048, 2048, (bf16*)(ws + WS_WOUT0), 0, scr, lane)) continue;
;         if (conv_matrix(it, a->in[21], 2048, 4608, (bf16*)(ws + WS_WIN1), 0, scr, lane)) continue;
;         if (conv_matrix(it, a->in[22], 2048, 2048, (bf16*)(ws + WS_WOUT1), 0, scr, lane)) continue;
;         if (conv_matrix(it, a->in[10], 2048, DFF, (bf16*)(ws + WS_WGU), 1, scr, lane)) continue;
;         if (conv_matrix(it, a->in[10] + (size_t)2048 * DFF, 2048, DFF, (bf16*)(ws + WS_WGU + 44 * MiB), 1, scr, lane)) continue;
;         if (conv_matrix(it, a->in[11], 2048, DFF, (bf16*)(ws + WS_WGU), 2, scr, lane)) continue;
;         if (conv_matrix(it, a->in[11] + (size_t)2048 * DFF, 2048, DFF, (bf16*)(ws + WS_WGU + 44 * MiB), 2, scr, lane)) continue;
;         if (conv_matrix(it, a->in[12], DFF, 2048, (bf16*)(ws + WS_WD), 0, scr, lane)) continue;
;         conv_matrix(it, a->in[12] + (size_t)2048 * DFF, DFF, 2048, (bf16*)(ws + WS_WD + 22 * MiB), 0, scr, lane);
;     }
; }
.Ldfb_36:
	v_mbcnt_lo_u32_b32 v2, -1, 0
	v_mbcnt_hi_u32_b32 v2, -1, v2
	s_sub_i32 s5, s87, 64
	s_lshl_b32 s5, s5, 3
	s_add_i32 s5, s5, 0x24c0
	v_readlane_b32 s4, v254, 48
	s_nop 1
	v_add_u32_e32 v0, s4, v2
	s_movk_i32 s33, 0x600
	v_readfirstlane_b32 s4, v0
	s_ashr_i32 s6, s4, 6
	s_add_i32 s99, s6, s5
	s_mov_b64 s[4:5], s[0:1]
	s_cmp_gt_i32 s99, 0x50ff
	s_cbranch_scc1 .Ldfb_exit
	s_load_dwordx2 s[8:9], s[4:5], 0xf0
	v_bfe_u32 v0, v2, 5, 1
	v_and_b32_e32 v28, 31, v2
	v_bfe_u32 v1, v2, 3, 3
	v_lshlrev_b32_e32 v2, 3, v2
	v_and_b32_e32 v2, 56, v2
	v_mov_b32_e32 v3, 0
	v_mul_u32_u24_e32 v6, 0x84, v2
	v_lshlrev_b32_e32 v2, 1, v2
	s_mul_i32 s10, s6, 0x2200
	s_waitcnt lgkmcnt(0)
	v_lshl_add_u64 v[22:23], s[8:9], 0, v[2:3]
	s_mov_b64 s[6:7], 0x100000
	s_add_i32 s11, s10, 0
	v_lshl_add_u64 v[4:5], v[22:23], 0, s[6:7]
	v_lshlrev_b32_e32 v2, 2, v1
	s_mov_b64 s[6:7], 0xc00000
	v_add3_u32 v44, s11, v6, v2
	v_lshl_add_u64 v[6:7], v[22:23], 0, s[6:7]
	s_mov_b64 s[6:7], 0xe00000
	v_lshl_add_u64 v[8:9], v[22:23], 0, s[6:7]
	s_mov_b64 s[6:7], 0x1000000
	v_lshl_add_u64 v[10:11], v[22:23], 0, s[6:7]
	s_mov_b64 s[6:7], 0x1800000
	v_lshl_add_u64 v[12:13], v[22:23], 0, s[6:7]
	s_mov_b64 s[6:7], 0x2a00000
	v_lshl_add_u64 v[14:15], v[22:23], 0, s[6:7]
	s_mov_b64 s[6:7], 0x3200000
	v_lshl_add_u64 v[16:17], v[22:23], 0, s[6:7]
	s_mov_b64 s[6:7], 0x5e00000
	v_lshl_add_u64 v[18:19], v[22:23], 0, s[6:7]
	s_mov_b64 s[6:7], 0x8a00000
	v_mul_u32_u24_e32 v2, 0x84, v0
	v_lshl_add_u64 v[20:21], v[22:23], 0, s[6:7]
	s_mov_b64 s[6:7], 0xa000000
	v_or_b32_e32 v2, s10, v2
	v_lshlrev_b32_e32 v24, 2, v28
	v_or_b32_e32 v45, 8, v1
	v_or_b32_e32 v46, 16, v1
	v_or_b32_e32 v47, 24, v1
	v_lshl_add_u64 v[22:23], v[22:23], 0, s[6:7]
	v_add3_u32 v48, v2, v24, 0
	v_mov_b32_e32 v25, v3
	v_or_b32_e32 v49, 14, v0
	v_or_b32_e32 v50, 12, v0
	v_or_b32_e32 v51, 10, v0
	v_or_b32_e32 v52, 8, v0
	v_or_b32_e32 v53, 6, v0
	v_or_b32_e32 v54, 4, v0
	v_or_b32_e32 v55, 2, v0
	v_or_b32_e32 v26, 0x2c00000, v24
	v_mov_b32_e32 v27, v3
	s_movk_i32 s23, 0x2900
	s_movk_i32 s24, 0x7fff
	s_mov_b32 s25, 0xffff0000
	s_movk_i32 s26, 0x1800
	s_movk_i32 s27, 0x4800
	s_movk_i32 s28, 0x1600
	s_movk_i32 s29, 0x5800
	s_mov_b64 s[6:7], 0x2c00000
	v_lshlrev_b32_e32 v2, 2, v28
	v_mov_b32_e32 v56, 0x4800
	v_mov_b32_e32 v57, 0x5800
	s_branch .Ldfb_39
.Ldfb_38:
	s_add_i32 s99, s99, s33
	s_cmp_lt_i32 s99, 0x5100
	s_cbranch_scc0 .Ldfb_exit
